# SSD chunk epilogue restaged 16-wide (same ops/order), 4 dwordx2 row stores -> 2 dwordx4 via permlane32_swap
# speedup vs baseline: 1.0024x; 1.0024x over previous
; __device__ __forceinline__ unsigned cvt_pk_bf16(float lo, float hi) { unsigned r; asm volatile("v_cvt_pk_bf16_f32 %0, %1, %2" : "=v"(r) : "v"(lo), "v"(hi)); return r; }
; __device__ __forceinline__ float silu_f(float x) { return x * sigm(x); }
; #define GAS __attribute__((address_space(1)))
; #define LAS __attribute__((address_space(3)))
; __device__ __forceinline__ void ssd_stream(const Frame& F, const Args& A, int sidx) {
;     ...
;         {
;             GAS unsigned char* yb = YGg + (size_t)t0 * 4096;
;             float ssq = 0.f;
; #pragma unroll
;             for (int q4 = 0; q4 < 4; ++q4) {
;                 const int p0 = 32 * pt + 8 * q4 + 4 * hh;
;                 const v2u xw = *(LAS v2u*)(XT + lcol * XS_ + p0 * 2);
;                 const float y0 = (Y[4 * q4 + 0] + Dsk * bflo(xw.x)) * silu_f(bflo(zw[q4].x)), y1 = (Y[4 * q4 + 1] + Dsk * bfhi(xw.x)) * silu_f(bfhi(zw[q4].x));
;                 const float y2 = (Y[4 * q4 + 2] + Dsk * bflo(xw.y)) * silu_f(bflo(zw[q4].y)), y3 = (Y[4 * q4 + 3] + Dsk * bfhi(xw.y)) * silu_f(bfhi(zw[q4].y));
;                 ssq += (y0 * y0 + y1 * y1) + (y2 * y2 + y3 * y3);
;                 v2u o; o.x = pg8::cvt_pk_bf16(y0, y1); o.y = pg8::cvt_pk_bf16(y2, y3);
;                 *(GAS v2u*)(yb + 16 * q4 + zoff) = o;
;             }
;             ssq += __shfl_xor(ssq, 32);
;             if (hh == 0) *(GAS float*)(SSQg + (size_t)t0 * 256 + soff) = ssq;
;         }
.LBB0_1312:
	ds_read_b64 v[36:37], v226
	ds_read_b64 v[38:39], v226 offset:16
	ds_read_b64 v[40:41], v226 offset:32
	ds_read_b64 v[42:43], v226 offset:48
	v_lshl_add_u64 v[34:35], v[154:155], 0, s[64:65]
	v_and_b32_e32 v46, 32, v202
	v_lshrrev_b32_e32 v46, 2, v46
	v_add_co_u32_e32 v34, vcc, v34, v46
	v_mov_b32_e32 v44, v141
	v_addc_co_u32_e32 v35, vcc, 0, v35, vcc
	v_mov_b32_e32 v45, v141
	s_waitcnt vmcnt(0)
	v_lshlrev_b32_e32 v98, 16, v184
	v_and_b32_e32 v99, 0xffff0000, v184
	v_lshlrev_b32_e32 v100, 16, v185
	v_and_b32_e32 v101, 0xffff0000, v185
	v_lshlrev_b32_e32 v102, 16, v182
	v_and_b32_e32 v103, 0xffff0000, v182
	v_lshlrev_b32_e32 v104, 16, v183
	v_and_b32_e32 v105, 0xffff0000, v183
	v_lshlrev_b32_e32 v106, 16, v180
	v_and_b32_e32 v107, 0xffff0000, v180
	v_lshlrev_b32_e32 v108, 16, v181
	v_and_b32_e32 v109, 0xffff0000, v181
	v_lshlrev_b32_e32 v110, 16, v178
	v_and_b32_e32 v111, 0xffff0000, v178
	v_lshlrev_b32_e32 v112, 16, v179
	v_and_b32_e32 v113, 0xffff0000, v179
	v_mul_f32_e32 v114, 0xbfb8aa3b, v98
	v_mul_f32_e32 v115, 0xbfb8aa3b, v99
	v_mul_f32_e32 v116, 0xbfb8aa3b, v100
	v_mul_f32_e32 v117, 0xbfb8aa3b, v101
	v_mul_f32_e32 v118, 0xbfb8aa3b, v102
	v_mul_f32_e32 v119, 0xbfb8aa3b, v103
	v_mul_f32_e32 v120, 0xbfb8aa3b, v104
	v_mul_f32_e32 v121, 0xbfb8aa3b, v105
	v_mul_f32_e32 v122, 0xbfb8aa3b, v106
	v_mul_f32_e32 v123, 0xbfb8aa3b, v107
	v_mul_f32_e32 v124, 0xbfb8aa3b, v108
	v_mul_f32_e32 v125, 0xbfb8aa3b, v109
	v_mul_f32_e32 v126, 0xbfb8aa3b, v110
	v_mul_f32_e32 v127, 0xbfb8aa3b, v111
	v_mul_f32_e32 v128, 0xbfb8aa3b, v112
	v_mul_f32_e32 v129, 0xbfb8aa3b, v113
	v_exp_f32_e32 v114, v114
	v_exp_f32_e32 v115, v115
	v_exp_f32_e32 v116, v116
	v_exp_f32_e32 v117, v117
	v_exp_f32_e32 v118, v118
	v_exp_f32_e32 v119, v119
	v_exp_f32_e32 v120, v120
	v_exp_f32_e32 v121, v121
	v_exp_f32_e32 v122, v122
	v_exp_f32_e32 v123, v123
	v_exp_f32_e32 v124, v124
	v_exp_f32_e32 v125, v125
	v_exp_f32_e32 v126, v126
	v_exp_f32_e32 v127, v127
	v_exp_f32_e32 v128, v128
	v_exp_f32_e32 v129, v129
	s_waitcnt lgkmcnt(0)
	v_lshlrev_b32_e32 v186, 16, v36
	v_and_b32_e32 v187, 0xffff0000, v36
	v_lshlrev_b32_e32 v188, 16, v37
	v_and_b32_e32 v189, 0xffff0000, v37
	v_lshlrev_b32_e32 v190, 16, v38
	v_and_b32_e32 v191, 0xffff0000, v38
	v_lshlrev_b32_e32 v192, 16, v39
	v_and_b32_e32 v193, 0xffff0000, v39
	v_lshlrev_b32_e32 v194, 16, v40
	v_and_b32_e32 v195, 0xffff0000, v40
	v_lshlrev_b32_e32 v196, 16, v41
	v_and_b32_e32 v197, 0xffff0000, v41
	v_lshlrev_b32_e32 v198, 16, v42
	v_and_b32_e32 v199, 0xffff0000, v42
	v_lshlrev_b32_e32 v200, 16, v43
	v_and_b32_e32 v201, 0xffff0000, v43
	v_add_f32_e32 v114, 1.0, v114
	v_add_f32_e32 v115, 1.0, v115
	v_add_f32_e32 v116, 1.0, v116
	v_add_f32_e32 v117, 1.0, v117
	v_add_f32_e32 v118, 1.0, v118
	v_add_f32_e32 v119, 1.0, v119
	v_add_f32_e32 v120, 1.0, v120
	v_add_f32_e32 v121, 1.0, v121
	v_add_f32_e32 v122, 1.0, v122
	v_add_f32_e32 v123, 1.0, v123
	v_add_f32_e32 v124, 1.0, v124
	v_add_f32_e32 v125, 1.0, v125
	v_add_f32_e32 v126, 1.0, v126
	v_add_f32_e32 v127, 1.0, v127
	v_add_f32_e32 v128, 1.0, v128
	v_add_f32_e32 v129, 1.0, v129
	v_rcp_f32_e32 v114, v114
	v_rcp_f32_e32 v115, v115
	v_rcp_f32_e32 v116, v116
	v_rcp_f32_e32 v117, v117
	v_rcp_f32_e32 v118, v118
	v_rcp_f32_e32 v119, v119
	v_rcp_f32_e32 v120, v120
	v_rcp_f32_e32 v121, v121
	v_rcp_f32_e32 v122, v122
	v_rcp_f32_e32 v123, v123
	v_rcp_f32_e32 v124, v124
	v_rcp_f32_e32 v125, v125
	v_rcp_f32_e32 v126, v126
	v_rcp_f32_e32 v127, v127
	v_rcp_f32_e32 v128, v128
	v_rcp_f32_e32 v129, v129
	v_pk_mul_f32 v[186:187], v[186:187], v[44:45]
	v_pk_mul_f32 v[188:189], v[188:189], v[44:45]
	v_pk_mul_f32 v[190:191], v[190:191], v[44:45]
	v_pk_mul_f32 v[192:193], v[192:193], v[44:45]
	v_pk_mul_f32 v[194:195], v[194:195], v[44:45]
	v_pk_mul_f32 v[196:197], v[196:197], v[44:45]
	v_pk_mul_f32 v[198:199], v[198:199], v[44:45]
	v_pk_mul_f32 v[200:201], v[200:201], v[44:45]
	v_pk_mul_f32 v[114:115], v[114:115], v[98:99]
	v_pk_mul_f32 v[116:117], v[116:117], v[100:101]
	v_pk_mul_f32 v[118:119], v[118:119], v[102:103]
	v_pk_mul_f32 v[120:121], v[120:121], v[104:105]
	v_pk_mul_f32 v[122:123], v[122:123], v[106:107]
	v_pk_mul_f32 v[124:125], v[124:125], v[108:109]
	v_pk_mul_f32 v[126:127], v[126:127], v[110:111]
	v_pk_mul_f32 v[128:129], v[128:129], v[112:113]
	v_pk_add_f32 v[18:19], v[18:19], v[186:187]
	v_pk_add_f32 v[20:21], v[20:21], v[188:189]
	v_pk_add_f32 v[22:23], v[22:23], v[190:191]
	v_pk_add_f32 v[24:25], v[24:25], v[192:193]
	v_pk_add_f32 v[26:27], v[26:27], v[194:195]
	v_pk_add_f32 v[28:29], v[28:29], v[196:197]
	v_pk_add_f32 v[30:31], v[30:31], v[198:199]
	v_pk_add_f32 v[32:33], v[32:33], v[200:201]
	v_pk_mul_f32 v[18:19], v[114:115], v[18:19]
	v_pk_mul_f32 v[20:21], v[116:117], v[20:21]
	v_pk_mul_f32 v[22:23], v[118:119], v[22:23]
	v_pk_mul_f32 v[24:25], v[120:121], v[24:25]
	v_pk_mul_f32 v[26:27], v[122:123], v[26:27]
	v_pk_mul_f32 v[28:29], v[124:125], v[28:29]
	v_pk_mul_f32 v[30:31], v[126:127], v[30:31]
	v_pk_mul_f32 v[32:33], v[128:129], v[32:33]
	v_cvt_pk_bf16_f32 v232, v18, v19
	v_cvt_pk_bf16_f32 v233, v20, v21
	v_cvt_pk_bf16_f32 v234, v22, v23
	v_cvt_pk_bf16_f32 v235, v24, v25
	v_cvt_pk_bf16_f32 v236, v26, v27
	v_cvt_pk_bf16_f32 v237, v28, v29
	v_cvt_pk_bf16_f32 v238, v30, v31
	v_cvt_pk_bf16_f32 v239, v32, v33
	v_mul_f32_e32 v130, v19, v19
	v_mul_f32_e32 v46, v21, v21
	v_mul_f32_e32 v131, v23, v23
	v_mul_f32_e32 v47, v25, v25
	v_mul_f32_e32 v132, v27, v27
	v_mul_f32_e32 v40, v29, v29
	v_mul_f32_e32 v133, v31, v31
	v_mul_f32_e32 v41, v33, v33
	v_fmac_f32_e32 v130, v18, v18
	v_fmac_f32_e32 v46, v20, v20
	v_fmac_f32_e32 v131, v22, v22
	v_fmac_f32_e32 v47, v24, v24
	v_fmac_f32_e32 v132, v26, v26
	v_fmac_f32_e32 v40, v28, v28
	v_fmac_f32_e32 v133, v30, v30
	v_fmac_f32_e32 v41, v32, v32
	v_add_f32_e32 v130, v130, v46
	v_add_f32_e32 v131, v131, v47
	v_add_f32_e32 v132, v132, v40
	v_add_f32_e32 v133, v133, v41
	v_permlane32_swap_b32_e32 v232, v234
	v_permlane32_swap_b32_e32 v233, v235
	v_permlane32_swap_b32_e32 v236, v238
	v_permlane32_swap_b32_e32 v237, v239
	v_add_f32_e32 v24, v130, v131
	v_add_f32_e32 v24, v24, v132
	v_mov_b32_e32 v19, v133
	global_store_dwordx4 v[34:35], v[232:235], off
	global_store_dwordx4 v[34:35], v[236:239], off offset:32
	v_and_b32_e32 v18, 64, v202
	v_xor_b32_e32 v20, 32, v202
	v_add_u32_e32 v21, 64, v18
	v_cmp_lt_i32_e32 vcc, v20, v21
	v_add_f32_e32 v19, v24, v19
	s_nop 0
	v_cndmask_b32_e32 v20, v202, v20, vcc
	v_lshlrev_b32_e32 v20, 2, v20
	ds_bpermute_b32 v20, v20, v19
	s_and_saveexec_b64 s[26:27], s[12:13]
	s_cbranch_execz .LBB0_1314
	s_lshl_b64 s[28:29], s[92:93], 8
	v_lshl_add_u64 v[22:23], v[156:157], 0, s[28:29]
	s_waitcnt lgkmcnt(0)
	v_add_f32_e32 v19, v19, v20
	global_store_dword v[22:23], v19, off
